# attention items handed out by an atomic ticket (largest first) instead of a static deal, so the shorter windowed items balance
# speedup vs baseline: 1.0869x; 1.0420x over previous
; __device__ __forceinline__ int get_bid() { int b = blockIdx.x; asm volatile("" : "+s"(b)); return b; }
; __device__ void run_phase(const Params& p, int ph, char* smem) {
;     ...
;         for (int r = 0; r < nr; ++r) {
;             if (l == 0 && quant_first) do_quant(r);
;             const int pos = (r & 1) ? (G - 1 - get_bid()) : get_bid();
;             const int si = r * G + pos;
;             if (si < 2048) attn_item(p, si, smem);
;             if (l == 0 && !quant_first) do_quant(r);
;         }
.LBB0_86:
	v_readlane_b32 s12, v167, 6
	s_mul_i32 s12, s28, s12
	s_add_i32 s11, s11, 1
	s_add_i32 s10, s10, s12
	v_readlane_b32 s12, v167, 3
	s_cmp_lt_u32 s11, s12
	s_cbranch_scc1 .LBB0_87
	v_mov_b32_e32 v0, 0x9c40
	ds_read_b32 v0, v0
	s_waitcnt lgkmcnt(0)
	v_readfirstlane_b32 s12, v0
	s_cmpk_gt_i32 s12, 0x7ff
	s_cbranch_scc1 .LBB0_140

; __device__ __forceinline__ int get_tid() { int t = threadIdx.x; asm volatile("" : "+v"(t)); return t; }
; __device__ __forceinline__ int get_bid() { int b = blockIdx.x; asm volatile("" : "+s"(b)); return b; }
; __device__ void attn_item(const Params& p, int s_idx, char* smem) {
;     const int qb = 63 - (s_idx >> 5), bh = s_idx & 31, b = bh >> 3, h = bh & 7;
;     const int tid = get_tid(), lane = tid & 63, wid = tid >> 6, ql = lane & 31, hh = lane >> 5;
;     const int qrow = qb * 128 + wid * 32 + ql;
;     const bf16_t* projb = p.proj + (size_t)b * S * NIN;
;     bf16x8 qf[4];
; #pragma unroll
;     for (int kk = 0; kk < 4; ++kk) qf[kk] = *(const bf16x8*)(projb + (size_t)qrow * NIN + h * 64 + kk * 16 + hh * 8);
;     f32x16 O0, O1;
; #pragma unroll
;     for (int i = 0; i < 16; ++i) { O0[i] = 0.f; O1[i] = 0.f; }
;     float mrun = -INFINITY, lsum = 0.f;
;     const int nkt = qb * 2 + 2;
;     const int wave_last = (qb * 128 + wid * 32 + 31) >> 6;
;     const int wave_q0 = qb * 128 + wid * 32;
;     const float sc = 0.125f * LOG2E;
;     struct KV { u32x4 rk[2], rv[2]; float rkb; };
;     KV sa;
;     auto gload = [&](int kt, KV& st) {
; #pragma unroll
;         for (int i = 0; i < 2; ++i) {
;             const int c = tid + 256 * i, key = c >> 3, dc = c & 7;
;             const bf16_t* src = projb + (size_t)(kt * 64 + key) * NIN + h * 64 + dc * 8;
;             st.rk[i] = *(const u32x4*)(src + 512);
;             const int keyv = c & 63, dcv = c >> 6;
;             st.rv[i] = *(const u32x4*)(projb + (size_t)(kt * 64 + keyv) * NIN + 1024 + h * 64 + dcv * 8);
;         }
;         st.rkb = p.kb[(size_t)bh * S + kt * 64 + (tid & 63)];
; __device__ void run_phase(const Params& p, int ph, char* smem) {
;     ...
;         for (int r = 0; r < nr; ++r) {
;             if (l == 0 && quant_first) do_quant(r);
;             const int pos = (r & 1) ? (G - 1 - get_bid()) : get_bid();
;             const int si = r * G + pos;
;             if (si < 2048) attn_item(p, si, smem);
.LBB0_101:
	s_waitcnt lgkmcnt(0)
	s_barrier
	v_cmp_eq_u32_e32 vcc, 0, v126
	s_and_saveexec_b64 s[98:99], vcc
	s_cbranch_execz .Ltk_skip
	v_readlane_b32 s12, v165, 2
	v_readlane_b32 s13, v165, 3
	v_readlane_b32 s15, v167, 36
	s_mul_i32 s15, s15, 0xc00
	s_addk_i32 s15, 0x840
	v_mov_b32_e32 v0, s15
	v_mov_b32_e32 v1, 1
	s_nop 2
	global_atomic_add v0, v0, v1, s[12:13] sc0
	v_mov_b32_e32 v1, 0x9c40
	s_waitcnt vmcnt(0)
	ds_write_b32 v1, v0
.Ltk_skip:
	s_or_b64 exec, exec, s[98:99]
	s_waitcnt lgkmcnt(0)
	s_barrier
	v_mov_b32_e32 v0, 0x9c40
	ds_read_b32 v0, v0
	s_waitcnt lgkmcnt(0)
	v_readfirstlane_b32 s15, v0
	s_cmpk_gt_i32 s15, 0x7ff
	s_cbranch_scc0 .LBB0_107
.LBB0_104:
	s_andn2_b64 vcc, exec, s[46:47]
	s_cbranch_vccnz .LBB0_86
	s_branch .LBB0_127
.LBB0_107:
	s_ashr_i32 s12, s15, 5
	s_lshl_b32 s13, s15, 10
	s_sub_i32 s14, 63, s12
	v_mov_b32_e32 v3, v126
	s_and_b32 s13, s13, 0x6000
	s_and_b32 s18, s15, 31
	s_lshl_b32 s12, s14, 7
	v_ashrrev_i32_e32 v143, 6, v3
	s_mul_i32 s16, s13, 0x1410
	v_lshlrev_b32_e32 v96, 5, v143
	s_add_u32 s34, s90, s16
	v_and_b32_e32 v2, 31, v3
	v_add_u32_e32 v144, s12, v96
	s_addc_u32 s35, s91, 0
	s_lshl_b32 s15, s15, 6
	v_or_b32_e32 v98, v144, v2
	s_waitcnt lgkmcnt(0)
	v_mov_b64_e32 v[0:1], s[34:35]
	s_and_b32 s15, s15, 0x1c0
	v_bfe_u32 v4, v3, 5, 1
	v_mad_i64_i32 v[6:7], s[16:17], v98, s29, v[0:1]
	s_lshl_b32 s22, s15, 1
	s_mov_b32 s23, s21
	v_lshl_add_u64 v[6:7], v[6:7], 0, s[22:23]
	v_lshlrev_b32_e32 v112, 4, v4
	v_lshl_add_u64 v[6:7], v[6:7], 0, v[112:113]
	v_ashrrev_i32_e32 v145, 3, v3
	v_lshlrev_b32_e32 v5, 3, v3
	global_load_dwordx4 v[64:67], v[6:7], off
	global_load_dwordx4 v[68:71], v[6:7], off offset:32
	global_load_dwordx4 v[72:75], v[6:7], off offset:64
	global_load_dwordx4 v[76:79], v[6:7], off offset:96
	v_readlane_b32 s98, v165, 2
	v_readlane_b32 s99, v165, 3
	v_readlane_b32 s32, v167, 36
	v_and_b32_e32 v32, 7, v130
	v_bfe_u32 v33, v130, 3, 1
	v_lshlrev_b32_e32 v32, 7, v32
	s_mul_i32 s32, s32, 0xc00
	v_lshl_or_b32 v32, v33, 10, v32
	v_mov_b32_e32 v33, s18
	s_add_i32 s32, s32, 32
	v_and_b32_e32 v33, 7, v33
	v_add_u32_e32 v32, s32, v32
	v_lshl_add_u32 v32, v33, 2, v32
	global_load_dword v34, v32, s[98:99] sc0 sc1
	s_lshl_b32 s32, s18, 15
	v_lshlrev_b32_e32 v35, 8, v130
	v_add_u32_e32 v35, s32, v35
	v_add_u32_e32 v38, 0x4000, v35
	s_lshl_b32 s32, s14, 9
	v_add_u32_e32 v39, s32, v35
	v_lshlrev_b32_e32 v33, 8, v130
	v_sub_u32_e32 v39, v39, v33
	v_readlane_b32 s98, v165, 40
	v_readlane_b32 s99, v165, 41
	s_nop 4
	s_nop 0
	global_load_dword v36, v35, s[98:99] offset:252
	global_load_dword v37, v38, s[98:99] offset:252
	global_load_dword v39, v39, s[98:99]
	s_waitcnt vmcnt(3)
	v_max_u32_dpp v34, v34, v34 quad_perm:[1,0,3,2] row_mask:0xf bank_mask:0xf
	s_nop 1
	v_max_u32_dpp v34, v34, v34 quad_perm:[2,3,0,1] row_mask:0xf bank_mask:0xf
	s_nop 1
	v_max_u32_dpp v34, v34, v34 row_half_mirror row_mask:0xf bank_mask:0xf
	s_waitcnt vmcnt(0)
	s_nop 0
	v_readlane_b32 s98, v34, 0
	v_readlane_b32 s99, v34, 8
	v_mov_b32_e32 v41, 0xbeb908c8
	s_nop 0
	v_mov_b32_e32 v40, s98
	v_mul_f32_e32 v40, s99, v40
	v_sqrt_f32_e32 v40, v40
	s_nop 0
	v_fma_f32 v40, v40, v41, v39
	v_add_f32_e32 v40, 0xc31b0000, v40
	v_cmp_lt_f32_e32 vcc, v36, v40
	s_bcnt1_i32_b64 s32, vcc
	v_cmp_lt_f32_e32 vcc, v37, v40
	s_bcnt1_i32_b64 s98, vcc
	s_add_i32 s32, s32, s98
	s_lshl_b32 s98, s14, 1
	s_min_i32 s32, s32, s98
	s_and_b32 s32, s32, -2
	s_lshl_b32 s98, s32, 6
	s_mul_i32 s99, s98, 0x1410
	s_add_u32 s34, s34, s99
	s_addc_u32 s35, s35, 0
	v_subrev_u32_e32 v98, s98, v98
	v_subrev_u32_e32 v144, s98, v144
	v_mov_b64_e32 v[0:1], s[34:35]
	v_mad_i64_i32 v[6:7], s[16:17], v145, s29, v[0:1]
	v_and_b32_e32 v5, 56, v5
	v_lshl_add_u64 v[6:7], v[6:7], 0, s[22:23]
	v_lshlrev_b32_e32 v112, 1, v5
	v_lshl_add_u64 v[6:7], v[6:7], 0, v[112:113]
	global_load_dwordx4 v[6:9], v[6:7], off offset:1024
	v_add_u32_e32 v5, 0x100, v3
	v_and_b32_e32 v114, 63, v3
	v_ashrrev_i32_e32 v146, 3, v5
	v_mul_u32_u24_e32 v10, 0x1410, v114
	v_mov_b32_e32 v11, v113
	v_mad_i64_i32 v[0:1], s[16:17], v146, s29, v[0:1]
	v_readlane_b32 s48, v165, 26
	v_lshl_add_u64 v[10:11], s[34:35], 0, v[10:11]
	v_and_b32_e32 v100, -8, v145
	v_lshl_add_u64 v[0:1], v[0:1], 0, s[22:23]
	v_and_b32_e32 v102, -8, v146
	s_lshl_b32 s15, s18, 15
	v_readlane_b32 s62, v165, 40
	v_lshl_add_u64 v[14:15], v[10:11], 0, s[22:23]
	v_ashrrev_i32_e32 v101, 31, v100
	v_lshl_add_u64 v[0:1], v[0:1], 0, v[112:113]
	v_ashrrev_i32_e32 v103, 31, v102
	v_readlane_b32 s63, v165, 41
	s_add_u32 s16, s62, s15
	v_lshl_add_u64 v[16:17], v[100:101], 1, v[14:15]
	global_load_dwordx4 v[10:13], v[0:1], off offset:1024
	v_lshl_add_u64 v[0:1], v[102:103], 1, v[14:15]
	s_addc_u32 s17, s63, 0
	s_lshl_b32 s99, s98, 2
	s_add_u32 s16, s16, s99
	s_addc_u32 s17, s17, 0
	v_lshlrev_b32_e32 v14, 2, v114
	v_mov_b32_e32 v15, v113
	s_movk_i32 s15, 0x90
	v_lshl_add_u64 v[104:105], s[16:17], 0, v[14:15]
	v_mad_u64_u32 v[106:107], s[16:17], v145, s15, v[112:113]
	v_mul_lo_u32 v5, v100, s15
	v_lshlrev_b32_e32 v14, 1, v114
	v_or_b32_e32 v107, v5, v14
	v_mad_u64_u32 v[108:109], s[16:17], v146, s15, v[112:113]
	v_mul_lo_u32 v5, v102, s15
	s_movk_i32 s44, 0x90
	v_or_b32_e32 v109, v5, v14
	v_cmp_gt_i32_e64 s[40:41], 64, v3
	v_lshlrev_b32_e32 v147, 2, v3
	v_readlane_b32 s49, v165, 27
	v_readlane_b32 s50, v165, 28
	v_readlane_b32 s51, v165, 29
	v_readlane_b32 s52, v165, 30
	v_readlane_b32 s53, v165, 31
	v_readlane_b32 s54, v165, 32
	v_readlane_b32 s55, v165, 33
	v_readlane_b32 s56, v165, 34
	v_readlane_b32 s57, v165, 35
	v_readlane_b32 s58, v165, 36
	v_readlane_b32 s59, v165, 37
	v_readlane_b32 s60, v165, 38
	v_readlane_b32 s61, v165, 39
	s_waitcnt vmcnt(1)
	ds_write_b128 v106, v[6:9]
	global_load_dwordx4 v[6:9], v[16:17], off offset:2048
	s_waitcnt vmcnt(0)
	ds_write_b16 v107, v6 offset:9216
	ds_write_b16_d16_hi v107, v6 offset:9360
	ds_write_b16 v107, v7 offset:9504
	ds_write_b16_d16_hi v107, v7 offset:9648
	ds_write_b16 v107, v8 offset:9792
	ds_write_b16_d16_hi v107, v8 offset:9936
	ds_write_b16 v107, v9 offset:10080
	ds_write_b16_d16_hi v107, v9 offset:10224
	global_load_dwordx4 v[6:9], v[0:1], off offset:2048
	ds_write_b128 v108, v[10:13]
	s_waitcnt vmcnt(0)
	ds_write_b16 v109, v6 offset:9216
	ds_write_b16_d16_hi v109, v6 offset:9360
	ds_write_b16 v109, v7 offset:9504
	ds_write_b16_d16_hi v109, v7 offset:9648
	ds_write_b16 v109, v8 offset:9792
	ds_write_b16_d16_hi v109, v8 offset:9936
	ds_write_b16 v109, v9 offset:10080
	ds_write_b16_d16_hi v109, v9 offset:10224
	s_and_saveexec_b64 s[24:25], s[40:41]
	s_cbranch_execz .LBB0_109
	global_load_dword v0, v[104:105], off
	s_waitcnt vmcnt(0)
	ds_write_b32 v147, v0 offset:18432
